# P0 table build: its per-stage global loads (six serial round trips behind kernarg s_loads) issued together at the top of the build
# speedup vs baseline: 1.0029x; 1.0025x over previous
; #define INP(k) ((const float*)(GAS const float*)KARG64(8 * (k)))
; __device__ __forceinline__ void ssm_tables(int g, int part, LAS float* L, bf16* __restrict__ TE, bf16* __restrict__ FT, float* __restrict__ LAM16) {
;     ...
;     const float dt = __expf(INP(6)[g]);
;     if (tid < 64) {
;         const int p = tid; const float are = INP(4)[g * 64 + p], aim = INP(5)[g * 64 + p];
;         for (int k = 0; k <= 16; ++k) {
;             const float mag = __expf(are * dt * (float)k);
;             float rev = aim * dt * (float)k * 0.15915494309189535f; rev -= rintf(rev);
;             lkr[k * 64 + p] = mag * __builtin_amdgcn_cosf(rev); lki[k * 64 + p] = mag * __builtin_amdgcn_sinf(rev);
;         }
;         const float lbr = lkr[64 + p], lbi = lki[64 + p], den = are * are + aim * aim, nre = lbr - 1.f;
;         fr_[p] = (nre * are + lbi * aim) / den; fi_[p] = (lbi * are - nre * aim) / den;
;         if (part == 0) { LAM16[(g * 64 + p) * 2] = lkr[16 * 64 + p]; LAM16[(g * 64 + p) * 2 + 1] = lki[16 * 64 + p]; }
;     }
;     __syncthreads();
;     for (int i = tid; i < 1024; i += 512) {
;         const int p = i >> 4; const float br = INP(7)[g * 1024 + i], bi = INP(8)[g * 1024 + i];
;         Bbr[i] = fr_[p] * br - fi_[p] * bi; Bbi[i] = fr_[p] * bi + fi_[p] * br;
;         Cr[i] = INP(9)[g * 1024 + i]; Ci[i] = INP(10)[g * 1024 + i];
.LBB0_9:
	s_mov_b64 s[10:11], s[0:1]
	s_load_dwordx2 s[14:15], s[10:11], 0xf0
	s_mov_b64 s[10:11], s[0:1]
	s_load_dwordx2 s[10:11], s[10:11], 0xf0
	s_ashr_i32 s12, s33, 3
	s_and_b32 s34, s33, 7
	s_load_dwordx2 s[60:61], s[0:1], 0x38
	s_load_dwordx2 s[62:63], s[0:1], 0x40
	s_load_dwordx2 s[64:65], s[0:1], 0x48
	s_load_dwordx2 s[66:67], s[0:1], 0x50
	s_load_dwordx2 s[72:73], s[0:1], 0x58
	s_lshl_b32 s70, s12, 10
	v_add_u32_e32 v92, s70, v218
	v_lshlrev_b32_e32 v92, 2, v92
	v_lshl_or_b32 v166, s12, 4, v10
	v_lshlrev_b32_e32 v166, 2, v166
	s_waitcnt lgkmcnt(0)
	global_load_dword v94, v92, s[60:61]
	global_load_dword v95, v92, s[62:63]
	global_load_dword v96, v92, s[64:65]
	global_load_dword v97, v92, s[66:67]
	global_load_dword v98, v92, s[60:61] offset:2048
	global_load_dword v99, v92, s[62:63] offset:2048
	global_load_dword v164, v92, s[64:65] offset:2048
	global_load_dword v165, v92, s[66:67] offset:2048
	global_load_dword v93, v166, s[72:73]
	s_mov_b64 s[18:19], s[0:1]
	s_mov_b64 s[20:21], s[0:1]
	s_and_saveexec_b64 s[16:17], s[4:5]
	s_cbranch_execz .LBB0_12
	s_load_dwordx2 s[20:21], s[20:21], 0x30
	s_ashr_i32 s13, s12, 31
	s_lshl_b64 s[38:39], s[12:13], 2
	s_mov_b64 s[36:37], s[0:1]
	v_lshl_or_b32 v4, s12, 6, v218
	s_waitcnt lgkmcnt(0)
	s_add_u32 s20, s20, s38
	s_addc_u32 s21, s21, s39
	global_load_dword v2, v3, s[20:21]
	s_load_dwordx2 s[20:21], s[36:37], 0x20
	v_ashrrev_i32_e32 v5, 31, v4
	v_lshlrev_b64 v[6:7], 2, v[4:5]
	s_cmp_lg_u32 s34, 0
	s_waitcnt lgkmcnt(0)
	v_lshl_add_u64 v[22:23], s[20:21], 0, v[6:7]
	s_mov_b64 s[20:21], s[0:1]
	global_load_dword v5, v[22:23], off
	s_load_dwordx2 s[20:21], s[20:21], 0x28
	s_waitcnt lgkmcnt(0)
	v_lshl_add_u64 v[6:7], s[20:21], 0, v[6:7]
	global_load_dword v22, v[6:7], off
	s_waitcnt vmcnt(2)
	v_mul_f32_e32 v2, 0x3fb8aa3b, v2
	v_exp_f32_e32 v2, v2
	s_waitcnt vmcnt(1)
	v_mul_f32_e32 v6, v2, v5
	v_mul_f32_e32 v7, 0, v6
	v_add_f32_e32 v24, v6, v6
	v_mul_f32_e32 v25, 0x40400000, v6
	v_mul_f32_e32 v23, 0x3fb8aa3b, v6
	v_mul_f32_e32 v26, 4.0, v6
	v_mul_f32_e32 v27, 0x40a00000, v6
	v_mul_f32_e32 v28, 0x40c00000, v6
	s_waitcnt vmcnt(0)
	v_mul_f32_e32 v30, v2, v22
	v_mul_f32_e32 v2, 0, v30
	v_add_f32_e32 v32, v30, v30
	v_mul_f32_e32 v33, 0x40400000, v30
	v_mul_f32_e32 v31, 0.15915494, v30
	v_mul_f32_e32 v34, 4.0, v30
	v_mul_f32_e32 v35, 0x40a00000, v30
	v_mul_f32_e32 v36, 0x40c00000, v30
	v_mul_f32_e32 v38, 0.15915494, v2
	v_mul_f32_e32 v39, 0.15915494, v32
	v_mul_f32_e32 v40, 0.15915494, v33
	v_mul_f32_e32 v37, 0x40e00000, v30
	v_rndne_f32_e32 v31, v31
	v_mul_f32_e32 v41, 0.15915494, v34
	v_mul_f32_e32 v42, 0.15915494, v35
	v_mul_f32_e32 v43, 0.15915494, v36
	v_rndne_f32_e32 v38, v38
	v_rndne_f32_e32 v39, v39
	v_rndne_f32_e32 v40, v40
	v_mul_f32_e32 v7, 0x3fb8aa3b, v7
	v_mul_f32_e32 v24, 0x3fb8aa3b, v24
	v_mul_f32_e32 v25, 0x3fb8aa3b, v25
	v_mul_f32_e32 v44, 0.15915494, v37
	v_fma_f32 v31, v30, 0.15915494, -v31
	v_rndne_f32_e32 v41, v41
	v_rndne_f32_e32 v42, v42
	v_rndne_f32_e32 v43, v43
	v_fma_f32 v2, v2, 0.15915494, -v38
	v_fma_f32 v32, v32, 0.15915494, -v39
	v_fma_f32 v33, v33, 0.15915494, -v40
	v_exp_f32_e32 v23, v23
	v_mul_f32_e32 v26, 0x3fb8aa3b, v26
	v_mul_f32_e32 v27, 0x3fb8aa3b, v27
	v_mul_f32_e32 v28, 0x3fb8aa3b, v28
	v_exp_f32_e32 v7, v7
	v_exp_f32_e32 v24, v24
	v_exp_f32_e32 v25, v25
	v_rndne_f32_e32 v44, v44
	v_cos_f32_e32 v38, v31
	v_fma_f32 v34, v34, 0.15915494, -v41
	v_fma_f32 v35, v35, 0.15915494, -v42
	v_fma_f32 v36, v36, 0.15915494, -v43
	v_cos_f32_e32 v39, v2
	v_sin_f32_e32 v2, v2
	v_cos_f32_e32 v40, v32
	v_sin_f32_e32 v32, v32
	v_cos_f32_e32 v41, v33
	v_exp_f32_e32 v26, v26
	v_exp_f32_e32 v27, v27
	v_exp_f32_e32 v28, v28
	v_sin_f32_e32 v31, v31
	v_fma_f32 v37, v37, 0.15915494, -v44
	v_sin_f32_e32 v33, v33
	v_cos_f32_e32 v42, v34
	v_sin_f32_e32 v34, v34
	v_cos_f32_e32 v43, v35
	v_sin_f32_e32 v35, v35
	v_cos_f32_e32 v44, v36
	v_sin_f32_e32 v36, v36
	v_mul_f32_e32 v29, 0x40e00000, v6
	v_mul_f32_e32 v29, 0x3fb8aa3b, v29
	v_mul_f32_e32 v46, v23, v38
	v_mul_f32_e32 v39, v7, v39
	v_mul_f32_e32 v47, v7, v2
	v_mul_f32_e32 v2, v24, v40
	v_mul_f32_e32 v7, v24, v32
	v_mul_f32_e32 v24, v25, v41
	v_exp_f32_e32 v29, v29
	v_cos_f32_e32 v45, v37
	v_mul_f32_e32 v31, v23, v31
	v_mul_f32_e32 v25, v25, v33
	v_mul_f32_e32 v32, v26, v42
	v_mul_f32_e32 v26, v26, v34
	v_mul_f32_e32 v33, v27, v43
	v_mul_f32_e32 v27, v27, v35
	v_mul_f32_e32 v34, v28, v44
	v_mul_f32_e32 v28, v28, v36
	ds_write2st64_b32 v1, v39, v46 offset1:1
	ds_write2st64_b32 v1, v31, v7 offset0:18 offset1:19
	ds_write2st64_b32 v1, v2, v24 offset0:2 offset1:3
	ds_write2st64_b32 v1, v25, v26 offset0:20 offset1:21
	ds_write2st64_b32 v1, v32, v33 offset0:4 offset1:5
	ds_write2st64_b32 v1, v27, v28 offset0:22 offset1:23
	v_mul_f32_e32 v24, 0x41000000, v30
	v_mul_f32_e32 v25, 0.15915494, v24
	v_mul_f32_e32 v7, 0x41000000, v6
	v_rndne_f32_e32 v25, v25
	v_mul_f32_e32 v7, 0x3fb8aa3b, v7
	v_fma_f32 v24, v24, 0.15915494, -v25
	v_mul_f32_e32 v27, 0x41100000, v30
	v_exp_f32_e32 v7, v7
	v_cos_f32_e32 v25, v24
	v_mul_f32_e32 v26, v29, v45
	v_sin_f32_e32 v24, v24
	v_mul_f32_e32 v28, 0.15915494, v27
	ds_write2st64_b32 v1, v34, v26 offset0:6 offset1:7
	v_mul_f32_e32 v26, 0x41100000, v6
	v_rndne_f32_e32 v28, v28
	v_sin_f32_e32 v2, v37
	v_mul_f32_e32 v26, 0x3fb8aa3b, v26
	v_fma_f32 v27, v27, 0.15915494, -v28
	v_exp_f32_e32 v26, v26
	v_cos_f32_e32 v28, v27
	v_mul_f32_e32 v25, v7, v25
	v_mul_f32_e32 v7, v7, v24
	v_sin_f32_e32 v24, v27
	v_mul_f32_e32 v2, v29, v2
	ds_write2st64_b32 v1, v2, v7 offset0:24 offset1:25
	v_mul_f32_e32 v2, v26, v28
	ds_write2st64_b32 v1, v25, v2 offset0:8 offset1:9
	v_mul_f32_e32 v2, v26, v24
	v_mul_f32_e32 v24, 0x41200000, v30
; __device__ __forceinline__ void ssm_tables(int g, int part, LAS float* L, bf16* __restrict__ TE, bf16* __restrict__ FT, float* __restrict__ LAM16) {
;     ...
;         for (int k = 0; k <= 16; ++k) {
;             const float mag = __expf(are * dt * (float)k);
;             float rev = aim * dt * (float)k * 0.15915494309189535f; rev -= rintf(rev);
;             lkr[k * 64 + p] = mag * __builtin_amdgcn_cosf(rev); lki[k * 64 + p] = mag * __builtin_amdgcn_sinf(rev);
;         }
;         const float lbr = lkr[64 + p], lbi = lki[64 + p], den = are * are + aim * aim, nre = lbr - 1.f;
;         fr_[p] = (nre * are + lbi * aim) / den; fi_[p] = (lbi * are - nre * aim) / den;
;         if (part == 0) { LAM16[(g * 64 + p) * 2] = lkr[16 * 64 + p]; LAM16[(g * 64 + p) * 2 + 1] = lki[16 * 64 + p]; }
;     }
;     __syncthreads();
	v_mul_f32_e32 v25, 0.15915494, v24
	v_mul_f32_e32 v7, 0x41200000, v6
	v_rndne_f32_e32 v25, v25
	v_mul_f32_e32 v27, 0x41300000, v30
	v_mul_f32_e32 v7, 0x3fb8aa3b, v7
	v_fma_f32 v24, v24, 0.15915494, -v25
	v_mul_f32_e32 v28, 0.15915494, v27
	v_exp_f32_e32 v7, v7
	v_cos_f32_e32 v25, v24
	v_sin_f32_e32 v24, v24
	v_mul_f32_e32 v26, 0x41300000, v6
	v_rndne_f32_e32 v28, v28
	v_mul_f32_e32 v26, 0x3fb8aa3b, v26
	v_fma_f32 v27, v27, 0.15915494, -v28
	v_exp_f32_e32 v26, v26
	v_cos_f32_e32 v28, v27
	v_mul_f32_e32 v25, v7, v25
	v_mul_f32_e32 v7, v7, v24
	ds_write2st64_b32 v1, v2, v7 offset0:26 offset1:27
	v_sin_f32_e32 v7, v27
	v_mul_f32_e32 v27, 0x41400000, v30
	v_mul_f32_e32 v2, v26, v28
	v_mul_f32_e32 v28, 0.15915494, v27
	v_mul_f32_e32 v24, 0x41400000, v6
	v_rndne_f32_e32 v28, v28
	v_mul_f32_e32 v24, 0x3fb8aa3b, v24
	v_fma_f32 v27, v27, 0.15915494, -v28
	v_exp_f32_e32 v24, v24
	v_cos_f32_e32 v28, v27
	v_sin_f32_e32 v27, v27
	ds_write2st64_b32 v1, v25, v2 offset0:10 offset1:11
	v_mul_f32_e32 v2, v26, v7
	v_mul_f32_e32 v7, v24, v28
	v_mul_f32_e32 v24, v24, v27
	ds_write2st64_b32 v1, v2, v24 offset0:28 offset1:29
	v_mul_f32_e32 v24, 0x41500000, v30
	v_mul_f32_e32 v25, 0.15915494, v24
	v_mul_f32_e32 v27, 0x41600000, v30
	v_mul_f32_e32 v2, 0x41500000, v6
	v_rndne_f32_e32 v25, v25
	v_mul_f32_e32 v28, 0.15915494, v27
	v_mul_f32_e32 v2, 0x3fb8aa3b, v2
	v_fma_f32 v24, v24, 0.15915494, -v25
	v_mul_f32_e32 v26, 0x41600000, v6
	v_rndne_f32_e32 v28, v28
	v_exp_f32_e32 v2, v2
	v_cos_f32_e32 v25, v24
	v_sin_f32_e32 v24, v24
	v_mul_f32_e32 v26, 0x3fb8aa3b, v26
	v_fma_f32 v27, v27, 0.15915494, -v28
	v_exp_f32_e32 v26, v26
	v_cos_f32_e32 v28, v27
	v_mul_f32_e32 v25, v2, v25
	v_mul_f32_e32 v2, v2, v24
	v_sin_f32_e32 v24, v27
	v_mul_f32_e32 v27, 0x41700000, v30
	ds_write2st64_b32 v1, v7, v25 offset0:12 offset1:13
	v_mul_f32_e32 v7, v26, v28
	v_mul_f32_e32 v28, 0.15915494, v27
	v_mul_f32_e32 v25, 0x41700000, v6
	v_rndne_f32_e32 v28, v28
	v_mul_f32_e32 v25, 0x3fb8aa3b, v25
	v_fma_f32 v27, v27, 0.15915494, -v28
	v_exp_f32_e32 v25, v25
	v_cos_f32_e32 v28, v27
	v_mul_f32_e32 v24, v26, v24
	v_sin_f32_e32 v26, v27
	ds_write2st64_b32 v1, v2, v24 offset0:30 offset1:31
	v_mul_f32_e32 v2, v25, v28
	ds_write2st64_b32 v1, v7, v2 offset0:14 offset1:15
	v_mul_f32_e32 v2, 0x41800000, v6
	v_mul_f32_e32 v6, 0x41800000, v30
	v_fma_f32 v23, v23, v38, -1.0
	v_mul_f32_e32 v24, v25, v26
	v_mul_f32_e32 v7, 0.15915494, v6
	v_mul_f32_e32 v25, v22, v22
	v_mul_f32_e32 v26, v5, v23
	v_rndne_f32_e32 v7, v7
	v_fmac_f32_e32 v25, v5, v5
	v_fmac_f32_e32 v26, v22, v31
	v_mul_f32_e32 v2, 0x3fb8aa3b, v2
	v_fma_f32 v7, v6, 0.15915494, -v7
	v_div_scale_f32 v27, s[20:21], v25, v25, v26
	v_exp_f32_e32 v2, v2
	v_cos_f32_e32 v6, v7
	v_sin_f32_e32 v7, v7
	v_rcp_f32_e32 v28, v27
	v_mul_f32_e32 v22, v22, v23
	v_fma_f32 v5, v5, v31, -v22
	v_pk_mul_f32 v[6:7], v[2:3], v[6:7] op_sel_hi:[0,1]
	v_fma_f32 v2, -v27, v28, 1.0
	v_fmac_f32_e32 v28, v2, v28
	v_div_scale_f32 v2, vcc, v26, v25, v26
	v_div_scale_f32 v22, s[20:21], v25, v25, v5
	ds_write2st64_b32 v1, v6, v47 offset0:16 offset1:17
	ds_write2st64_b32 v1, v24, v7 offset0:32 offset1:33
	v_mul_f32_e32 v24, v2, v28
	v_rcp_f32_e32 v23, v22
	v_fma_f32 v29, -v27, v24, v2
	v_fmac_f32_e32 v24, v29, v28
	v_fma_f32 v2, -v27, v24, v2
	v_div_fmas_f32 v2, v2, v28, v24
	v_fma_f32 v24, -v22, v23, 1.0
	v_fmac_f32_e32 v23, v24, v23
	v_div_scale_f32 v24, vcc, v5, v25, v5
	v_div_fixup_f32 v2, v2, v25, v26
	v_mul_f32_e32 v26, v24, v23
	v_fma_f32 v27, -v22, v26, v24
	v_fmac_f32_e32 v26, v27, v23
	v_fma_f32 v22, -v22, v26, v24
	v_div_fmas_f32 v22, v22, v23, v26
	v_div_fixup_f32 v5, v22, v25, v5
	ds_write2st64_b32 v1, v2, v5 offset0:34 offset1:35
	s_cbranch_scc1 .LBB0_12
	s_load_dwordx2 s[18:19], s[18:19], 0xf0
	v_lshlrev_b32_e32 v4, 1, v4
	v_ashrrev_i32_e32 v5, 31, v4
	s_waitcnt lgkmcnt(0)
	v_lshl_add_u64 v[4:5], v[4:5], 2, s[18:19]
	v_add_co_u32_e32 v4, vcc, 0x54000, v4
	s_nop 1
	v_addc_co_u32_e32 v5, vcc, 0, v5, vcc
	global_store_dwordx2 v[4:5], v[6:7], off
.LBB0_12:
	s_or_b64 exec, exec, s[16:17]
	s_waitcnt vmcnt(0)
	s_lshl_b32 s13, s12, 10
	s_mov_b64 s[16:17], 0
	v_mov_b32_e32 v2, v12
	v_mov_b32_e32 v4, v11
	v_mov_b32_e32 v5, v218
	s_waitcnt lgkmcnt(0)
	s_barrier
; #define INP(k) ((const float*)(GAS const float*)KARG64(8 * (k)))
; __device__ __forceinline__ void ssm_tables(int g, int part, LAS float* L, bf16* __restrict__ TE, bf16* __restrict__ FT, float* __restrict__ LAM16) {
;     ...
;     for (int i = tid; i < 1024; i += 512) {
;         const int p = i >> 4; const float br = INP(7)[g * 1024 + i], bi = INP(8)[g * 1024 + i];
;         Bbr[i] = fr_[p] * br - fi_[p] * bi; Bbi[i] = fr_[p] * bi + fi_[p] * br;
;         Cr[i] = INP(9)[g * 1024 + i]; Ci[i] = INP(10)[g * 1024 + i];
;     }
;     __syncthreads();
;     {
;         const int k = tid >> 5, cl = (tid >> 4) & 1, c = 2 * part + cl, c2 = tid & 15; float s = 0.f;
;         for (int p = 0; p < 64; ++p) {
;             const float cr = Cr[c * 64 + p], ci = Ci[c * 64 + p], lr = lkr[k * 64 + p], li = lki[k * 64 + p];
;             const float xr = cr * lr - ci * li, xi = cr * li + ci * lr;
;             s += xr * Bbr[p * 16 + c2] - xi * Bbi[p * 16 + c2];
;         }
;         if (k == 0 && c == c2) s += INP(11)[g * 16 + c];
;         Kt[tid] = s;
;     }
.LBB0_13:
	s_mov_b64 s[18:19], s[0:1]
	v_add_u32_e32 v6, s13, v5
	v_ashrrev_i32_e32 v7, 31, v6
	v_lshlrev_b64 v[6:7], 2, v[6:7]
	s_mov_b64 s[20:21], s[0:1]
	s_waitcnt lgkmcnt(0)
	v_mov_b32_e32 v24, v94
	v_cmp_lt_u32_e32 vcc, s23, v5
	s_or_b64 s[16:17], vcc, s[16:17]
	s_waitcnt lgkmcnt(0)
	v_mov_b32_e32 v22, v95
	ds_read_b32 v23, v2 offset:256
	ds_read_b32 v25, v2
	s_mov_b64 s[18:19], s[0:1]
	s_waitcnt vmcnt(0) lgkmcnt(1)
	v_mul_f32_e32 v23, v22, v23
	s_waitcnt lgkmcnt(0)
	v_fma_f32 v23, v24, v25, -v23
	ds_write_b32 v4, v23
	ds_read_b32 v23, v2 offset:256
	ds_read_b32 v25, v2
	v_add_u32_e32 v2, 0x80, v2
	s_waitcnt lgkmcnt(1)
	v_mul_f32_e32 v23, v24, v23
	s_waitcnt lgkmcnt(0)
	v_fmac_f32_e32 v23, v22, v25
	ds_write_b32 v4, v23 offset:4096
	s_waitcnt lgkmcnt(0)
	v_mov_b32_e32 v22, v96
	s_mov_b64 s[18:19], s[0:1]
	s_waitcnt vmcnt(0)
	ds_write_b32 v4, v22 offset:8192
	s_waitcnt lgkmcnt(0)
	v_mov_b32_e32 v6, v97
	v_add_u32_e32 v7, 0x200, v5
	v_mov_b32_e32 v5, v7
	s_waitcnt vmcnt(0)
	ds_write_b32 v4, v6 offset:12288
	v_add_u32_e32 v4, 0x800, v4
	v_mov_b32_e32 v94, v98
	v_mov_b32_e32 v95, v99
	v_mov_b32_e32 v96, v164
	v_mov_b32_e32 v97, v165
	s_andn2_b64 exec, exec, s[16:17]
	s_cbranch_execnz .LBB0_13
	s_or_b64 exec, exec, s[16:17]
	s_and_b32 s13, s31, 7
	v_lshl_add_u32 v4, s13, 9, v16
	v_mov_b32_e32 v2, 0
	s_mov_b32 s13, 0
	v_mov_b32_e32 v5, v15
	s_waitcnt lgkmcnt(0)
	s_barrier
.LBB0_15:
	v_add_u32_e32 v26, s13, v4
	v_add_u32_e32 v34, s13, v14
	v_add_u32_e32 v42, 0x1000, v5
	ds_read2_b32 v[6:7], v5 offset1:16
	ds_read2_b32 v[38:39], v5 offset0:32 offset1:48
	ds_read_b128 v[22:25], v26
	ds_read_b128 v[26:29], v26 offset:4096
	ds_read_b128 v[30:33], v34
	ds_read_b128 v[34:37], v34 offset:4352
	ds_read2_b32 v[40:41], v42 offset1:16
	ds_read2_b32 v[42:43], v42 offset0:32 offset1:48
	s_waitcnt lgkmcnt(4)
	v_mov_b32_e32 v46, v26
	v_mov_b32_e32 v47, v22
	v_mov_b32_e32 v22, v27
	s_waitcnt lgkmcnt(2)
	v_pk_mul_f32 v[52:53], v[46:47], v[34:35] op_sel_hi:[1,0]
	v_mov_b32_e32 v26, v31
	v_mov_b32_e32 v48, v28
	v_mov_b32_e32 v49, v24
	v_mov_b32_e32 v24, v29
	v_mov_b32_e32 v28, v37
	v_pk_mul_f32 v[34:35], v[22:23], v[34:35] op_sel:[0,1]
	v_pk_fma_f32 v[54:55], v[46:47], v[30:31], v[52:53] op_sel:[1,0,0] op_sel_hi:[0,1,1] neg_lo:[0,0,1] neg_hi:[0,0,1]
	v_pk_fma_f32 v[46:47], v[46:47], v[30:31], v[52:53] op_sel:[1,0,0] op_sel_hi:[0,0,1]
	v_mov_b32_e32 v44, v6
	v_mov_b32_e32 v6, v38
	s_waitcnt lgkmcnt(1)
	v_mov_b32_e32 v45, v40
	v_mov_b32_e32 v38, v33
	v_mov_b32_e32 v50, v33
	v_pk_mul_f32 v[36:37], v[48:49], v[36:37] op_sel_hi:[1,0]
	v_pk_mul_f32 v[28:29], v[24:25], v[28:29] op_sel_hi:[1,0]
	v_pk_fma_f32 v[26:27], v[22:23], v[26:27], v[34:35] op_sel:[1,0,0] op_sel_hi:[0,1,1] neg_lo:[0,0,1] neg_hi:[0,0,1]
	v_pk_fma_f32 v[22:23], v[22:23], v[30:31], v[34:35] op_sel:[1,1,0] op_sel_hi:[0,1,1]
	v_mov_b32_e32 v55, v47
	v_mov_b32_e32 v40, v7
	v_pk_fma_f32 v[30:31], v[48:49], v[32:33], v[36:37] op_sel:[1,0,0] op_sel_hi:[0,1,1] neg_lo:[0,0,1] neg_hi:[0,0,1]
	v_pk_fma_f32 v[32:33], v[48:49], v[32:33], v[36:37] op_sel:[1,0,0] op_sel_hi:[0,0,1]
	v_pk_fma_f32 v[34:35], v[24:25], v[38:39], v[28:29] op_sel:[1,0,0] op_sel_hi:[0,1,1] neg_lo:[0,0,1] neg_hi:[0,0,1]
	v_pk_fma_f32 v[24:25], v[24:25], v[50:51], v[28:29] op_sel:[1,0,0] op_sel_hi:[0,0,1]
	v_mov_b32_e32 v27, v23
	v_pk_mul_f32 v[22:23], v[44:45], v[54:55]
	s_waitcnt lgkmcnt(0)
	v_mov_b32_e32 v7, v42
	v_mov_b32_e32 v31, v33
	v_mov_b32_e32 v35, v25
	v_pk_mul_f32 v[24:25], v[40:41], v[26:27]
	v_sub_f32_e32 v22, v22, v23
	v_mov_b32_e32 v42, v39
	v_pk_mul_f32 v[6:7], v[6:7], v[30:31]
	v_sub_f32_e32 v23, v24, v25
	v_add_f32_e32 v2, v2, v22
	v_pk_mul_f32 v[26:27], v[42:43], v[34:35]
	v_sub_f32_e32 v6, v6, v7
	v_add_f32_e32 v2, v2, v23
	s_add_i32 s13, s13, 16
	v_sub_f32_e32 v7, v26, v27
	v_add_f32_e32 v2, v2, v6
	v_add_u32_e32 v5, 0x100, v5
	s_cmpk_eq_i32 s13, 0x100
	v_add_f32_e32 v2, v2, v7
	s_cbranch_scc0 .LBB0_15
	s_lshl_b32 s36, s34, 1
	v_or_b32_e32 v4, s36, v9
	v_cmp_eq_u32_e32 vcc, v4, v10
	s_and_b64 s[18:19], s[6:7], vcc
	s_and_saveexec_b64 s[16:17], s[18:19]
	s_cbranch_execz .LBB0_18
	s_mov_b64 s[18:19], s[0:1]
	v_add_f32_e32 v2, v2, v93
